# seam conversion loads as 8 dwordx4 per tile (10 VMEM per item, all three items in flight under the 63-deep vmcnt) instead of 32 dword loads
# speedup vs baseline: 1.0042x; 1.0042x over previous
.LBB0_253:
	s_cmp_gt_i32 s29, 1
	s_cselect_b64 s[0:1], -1, 0
	s_and_b64 s[4:5], s[60:61], s[0:1]
	s_andn2_b64 vcc, exec, s[4:5]
	s_cbranch_vccnz .LBB0_303
	s_waitcnt vmcnt(0)
	v_cmp_eq_u32_e32 vcc, 0, v208
	s_waitcnt lgkmcnt(0)
	s_barrier
	v_readfirstlane_b32 s3, v208
	s_nop 3
	s_lshr_b32 s3, s3, 6
	s_cmp_eq_u32 s3, 0
	s_cbranch_scc1 .Lmy_cv0_end
	v_readlane_b32 s36, v237, 0
	v_readlane_b32 s37, v237, 1
	s_mul_i32 s4, s2, 7
	s_add_i32 s4, s4, s3
	s_add_i32 s4, s4, -1
	s_lshl_b32 s72, s3, 14
	s_mov_b32 s3, s4
	s_nop 4
	s_load_dwordx4 s[60:63], s[36:37], 0x60
	s_load_dwordx2 s[64:65], s[36:37], 0x70
	s_load_dwordx2 s[98:99], s[36:37], 0x58
	s_load_dwordx2 s[100:101], s[36:37], 0x48
	v_and_b32_e32 v8, 7, v209
	v_lshrrev_b32_e32 v9, 3, v209
	v_mul_u32_u24_e32 v0, 0x5800, v9
	v_lshl_add_u32 v0, v8, 4, v0
	v_lshlrev_b32_e32 v152, 13, v9
	v_lshl_add_u32 v152, v8, 4, v152
	v_mul_u32_u24_e32 v2, 0x420, v8
	v_lshl_add_u32 v2, v9, 2, v2
	v_add_u32_e32 v2, s72, v2
	v_mul_u32_u24_e32 v3, 0x108, v9
	v_lshl_add_u32 v3, v8, 5, v3
	v_add_u32_e32 v3, s72, v3
	v_lshlrev_b32_e32 v4, 12, v9
	v_lshl_add_u32 v4, v8, 4, v4
	v_lshlrev_b32_e32 v5, 5, v8
	s_waitcnt lgkmcnt(0)
	s_add_i32 s66, s3, 256
	s_lshr_b32 vcc_lo, s66, 6
	s_and_b32 vcc_hi, s66, 63
	s_lshl_b32 s70, vcc_lo, 19
	s_lshl_b32 s71, vcc_hi, 7
	s_add_u32 s68, s98, s70
	s_addc_u32 s69, s99, 0
	s_add_u32 s68, s68, s71
	s_addc_u32 s69, s69, 0
	v_mov_b32_e32 v1, v152
	global_load_dwordx4 v[112:115], v1, s[68:69] nt
	v_add_u32_e32 v1, 0x10000, v1
	global_load_dwordx4 v[116:119], v1, s[68:69] nt
	v_add_u32_e32 v1, 0x10000, v1
	global_load_dwordx4 v[120:123], v1, s[68:69] nt
	v_add_u32_e32 v1, 0x10000, v1
	global_load_dwordx4 v[124:127], v1, s[68:69] nt
	v_add_u32_e32 v1, 0x10000, v1
	global_load_dwordx4 v[128:131], v1, s[68:69] nt
	v_add_u32_e32 v1, 0x10000, v1
	global_load_dwordx4 v[132:135], v1, s[68:69] nt
	v_add_u32_e32 v1, 0x10000, v1
	global_load_dwordx4 v[136:139], v1, s[68:69] nt
	v_add_u32_e32 v1, 0x10000, v1
	global_load_dwordx4 v[140:143], v1, s[68:69] nt
	s_and_b32 s70, vcc_lo, 1
	s_lshl_b32 s70, s70, 8
	s_add_u32 s70, s100, s70
	s_addc_u32 s71, s101, 0
	global_load_dwordx4 v[144:147], v5, s[70:71]
	global_load_dwordx4 v[148:151], v5, s[70:71] offset:16
	s_add_i32 s66, s3, 512
	s_cmpk_ge_u32 s66, 0x1600
	s_cselect_b32 s68, s64, s62
	s_cselect_b32 s69, s65, s63
	s_cselect_b32 s54, 128, 0
	s_cselect_b32 s41, 0x1600, 0
	s_sub_u32 s41, s66, s41
	s_mul_hi_u32 s4, s41, 0xba2e8ba3
	s_lshr_b32 s4, s4, 7
	s_mul_i32 s70, s4, 0xb0
	s_sub_u32 s5, s41, s70
	s_mul_i32 s70, s4, 0x160000
	s_lshl_b32 s71, s5, 7
	s_add_u32 s68, s68, s70
	s_addc_u32 s69, s69, 0
	s_add_u32 s68, s68, s71
	s_addc_u32 s69, s69, 0
	v_mov_b32_e32 v1, v0
	global_load_dwordx4 v[32:35], v1, s[68:69] nt
	v_add_u32_e32 v1, 0x2c000, v1
	global_load_dwordx4 v[36:39], v1, s[68:69] nt
	v_add_u32_e32 v1, 0x2c000, v1
	global_load_dwordx4 v[40:43], v1, s[68:69] nt
	v_add_u32_e32 v1, 0x2c000, v1
	global_load_dwordx4 v[44:47], v1, s[68:69] nt
	v_add_u32_e32 v1, 0x2c000, v1
	global_load_dwordx4 v[48:51], v1, s[68:69] nt
	v_add_u32_e32 v1, 0x2c000, v1
	global_load_dwordx4 v[52:55], v1, s[68:69] nt
	v_add_u32_e32 v1, 0x2c000, v1
	global_load_dwordx4 v[56:59], v1, s[68:69] nt
	v_add_u32_e32 v1, 0x2c000, v1
	global_load_dwordx4 v[60:63], v1, s[68:69] nt
	s_lshl_b32 s70, s4, 8
	s_add_u32 s70, s60, s70
	s_addc_u32 s71, s61, 0
	global_load_dwordx4 v[96:99], v5, s[70:71]
	global_load_dwordx4 v[100:103], v5, s[70:71] offset:16
	s_addk_i32 s66, 0x700
	s_cmpk_ge_u32 s66, 0x1600
	s_cselect_b32 s68, s64, s62
	s_cselect_b32 s69, s65, s63
	s_cselect_b32 s40, 128, 0
	s_cselect_b32 s41, 0x1600, 0
	s_sub_u32 s41, s66, s41
	s_mul_hi_u32 s55, s41, 0xba2e8ba3
	s_lshr_b32 s55, s55, 7
	s_mul_i32 s70, s55, 0xb0
	s_sub_u32 s67, s41, s70
	s_mul_i32 s70, s55, 0x160000
	s_lshl_b32 s71, s67, 7
	s_add_u32 s68, s68, s70
	s_addc_u32 s69, s69, 0
	s_add_u32 s68, s68, s71
	s_addc_u32 s69, s69, 0
	v_mov_b32_e32 v1, v0
	global_load_dwordx4 v[64:67], v1, s[68:69] nt
	v_add_u32_e32 v1, 0x2c000, v1
	global_load_dwordx4 v[68:71], v1, s[68:69] nt
	v_add_u32_e32 v1, 0x2c000, v1
	global_load_dwordx4 v[72:75], v1, s[68:69] nt
	v_add_u32_e32 v1, 0x2c000, v1
	global_load_dwordx4 v[76:79], v1, s[68:69] nt
	v_add_u32_e32 v1, 0x2c000, v1
	global_load_dwordx4 v[80:83], v1, s[68:69] nt
	v_add_u32_e32 v1, 0x2c000, v1
	global_load_dwordx4 v[84:87], v1, s[68:69] nt
	v_add_u32_e32 v1, 0x2c000, v1
	global_load_dwordx4 v[88:91], v1, s[68:69] nt
	v_add_u32_e32 v1, 0x2c000, v1
	global_load_dwordx4 v[92:95], v1, s[68:69] nt
	s_lshl_b32 s70, s55, 8
	s_add_u32 s70, s60, s70
	s_addc_u32 s71, s61, 0
	global_load_dwordx4 v[104:107], v5, s[70:71]
	global_load_dwordx4 v[108:111], v5, s[70:71] offset:16
	s_waitcnt vmcnt(20)
	s_waitcnt lgkmcnt(0)
	ds_write_b32 v2, v112 offset:0
	ds_write_b32 v2, v113 offset:264
	ds_write_b32 v2, v114 offset:528
	ds_write_b32 v2, v115 offset:792
	ds_write_b32 v2, v116 offset:32
	ds_write_b32 v2, v117 offset:296
	ds_write_b32 v2, v118 offset:560
	ds_write_b32 v2, v119 offset:824
	ds_write_b32 v2, v120 offset:64
	ds_write_b32 v2, v121 offset:328
	ds_write_b32 v2, v122 offset:592
	ds_write_b32 v2, v123 offset:856
	ds_write_b32 v2, v124 offset:96
	ds_write_b32 v2, v125 offset:360
	ds_write_b32 v2, v126 offset:624
	ds_write_b32 v2, v127 offset:888
	ds_write_b32 v2, v128 offset:128
	ds_write_b32 v2, v129 offset:392
	ds_write_b32 v2, v130 offset:656
	ds_write_b32 v2, v131 offset:920
	ds_write_b32 v2, v132 offset:160
	ds_write_b32 v2, v133 offset:424
	ds_write_b32 v2, v134 offset:688
	ds_write_b32 v2, v135 offset:952
	ds_write_b32 v2, v136 offset:192
	ds_write_b32 v2, v137 offset:456
	ds_write_b32 v2, v138 offset:720
	ds_write_b32 v2, v139 offset:984
	ds_write_b32 v2, v140 offset:224
	ds_write_b32 v2, v141 offset:488
	ds_write_b32 v2, v142 offset:752
	ds_write_b32 v2, v143 offset:1016
	s_cmp_lt_u32 vcc_lo, 16
	s_cbranch_scc0 .Lmy_cv0_ns
	v_mul_f32_e32 v144, 0x3f4ccccd, v144
	v_mul_f32_e32 v145, 0x3f4ccccd, v145
	v_mul_f32_e32 v146, 0x3f4ccccd, v146
	v_mul_f32_e32 v147, 0x3f4ccccd, v147
	v_mul_f32_e32 v148, 0x3f4ccccd, v148
	v_mul_f32_e32 v149, 0x3f4ccccd, v149
	v_mul_f32_e32 v150, 0x3f4ccccd, v150
	v_mul_f32_e32 v151, 0x3f4ccccd, v151
	s_branch .Lmy_cv0_sd

.Lmy_cv0_sd:
	s_lshl_b32 s70, vcc_hi, 17
	s_lshl_b32 s71, vcc_lo, 7
	s_add_i32 s70, s70, s71
	s_add_u32 s70, s70, 0x1a00000
	s_add_u32 s70, s26, s70
	s_addc_u32 s71, s27, 0
	s_waitcnt lgkmcnt(0)
	ds_read_b64 v[160:161], v3 offset:0
	ds_read_b64 v[162:163], v3 offset:8
	ds_read_b64 v[164:165], v3 offset:16
	ds_read_b64 v[166:167], v3 offset:24
	ds_read_b64 v[168:169], v3 offset:2112
	ds_read_b64 v[170:171], v3 offset:2120
	ds_read_b64 v[172:173], v3 offset:2128
	ds_read_b64 v[174:175], v3 offset:2136
	ds_read_b64 v[176:177], v3 offset:4224
	ds_read_b64 v[178:179], v3 offset:4232
	ds_read_b64 v[180:181], v3 offset:4240
	ds_read_b64 v[182:183], v3 offset:4248
	ds_read_b64 v[184:185], v3 offset:6336
	ds_read_b64 v[186:187], v3 offset:6344
	ds_read_b64 v[188:189], v3 offset:6352
	ds_read_b64 v[190:191], v3 offset:6360
	s_waitcnt lgkmcnt(12)
	v_mul_f32_e32 v160, v160, v144
	v_mul_f32_e32 v161, v161, v145
	v_mul_f32_e32 v162, v162, v146
	v_mul_f32_e32 v163, v163, v147
	v_mul_f32_e32 v164, v164, v148
	v_mul_f32_e32 v165, v165, v149
	v_mul_f32_e32 v166, v166, v150
	v_mul_f32_e32 v167, v167, v151
	v_cvt_pk_bf16_f32 v192, v160, v161
	v_cvt_pk_bf16_f32 v193, v162, v163
	v_cvt_pk_bf16_f32 v194, v164, v165
	v_cvt_pk_bf16_f32 v195, v166, v167
	v_mov_b32_e32 v9, v4
	global_store_dwordx4 v9, v[192:195], s[70:71]
	s_waitcnt lgkmcnt(8)
	v_mul_f32_e32 v168, v168, v144
	v_mul_f32_e32 v169, v169, v145
	v_mul_f32_e32 v170, v170, v146
	v_mul_f32_e32 v171, v171, v147
	v_mul_f32_e32 v172, v172, v148
	v_mul_f32_e32 v173, v173, v149
	v_mul_f32_e32 v174, v174, v150
	v_mul_f32_e32 v175, v175, v151
	v_cvt_pk_bf16_f32 v196, v168, v169
	v_cvt_pk_bf16_f32 v197, v170, v171
	v_cvt_pk_bf16_f32 v198, v172, v173
	v_cvt_pk_bf16_f32 v199, v174, v175
	v_add_u32_e32 v9, 0x8000, v9
	global_store_dwordx4 v9, v[196:199], s[70:71]
	s_waitcnt lgkmcnt(4)
	v_mul_f32_e32 v176, v176, v144
	v_mul_f32_e32 v177, v177, v145
	v_mul_f32_e32 v178, v178, v146
	v_mul_f32_e32 v179, v179, v147
	v_mul_f32_e32 v180, v180, v148
	v_mul_f32_e32 v181, v181, v149
	v_mul_f32_e32 v182, v182, v150
	v_mul_f32_e32 v183, v183, v151
	v_cvt_pk_bf16_f32 v200, v176, v177
	v_cvt_pk_bf16_f32 v201, v178, v179
	v_cvt_pk_bf16_f32 v202, v180, v181
	v_cvt_pk_bf16_f32 v203, v182, v183
	v_add_u32_e32 v9, 0x8000, v9
	global_store_dwordx4 v9, v[200:203], s[70:71]
	s_waitcnt lgkmcnt(0)
	v_mul_f32_e32 v184, v184, v144
	v_mul_f32_e32 v185, v185, v145
	v_mul_f32_e32 v186, v186, v146
	v_mul_f32_e32 v187, v187, v147
	v_mul_f32_e32 v188, v188, v148
	v_mul_f32_e32 v189, v189, v149
	v_mul_f32_e32 v190, v190, v150
	v_mul_f32_e32 v191, v191, v151
	v_cvt_pk_bf16_f32 v204, v184, v185
	v_cvt_pk_bf16_f32 v205, v186, v187
	v_cvt_pk_bf16_f32 v206, v188, v189
	v_cvt_pk_bf16_f32 v207, v190, v191
	v_add_u32_e32 v9, 0x8000, v9
	global_store_dwordx4 v9, v[204:207], s[70:71]
	s_waitcnt vmcnt(10)
	s_waitcnt lgkmcnt(0)
	ds_write_b32 v2, v32 offset:0
	ds_write_b32 v2, v33 offset:264
	ds_write_b32 v2, v34 offset:528
	ds_write_b32 v2, v35 offset:792
	ds_write_b32 v2, v36 offset:32
	ds_write_b32 v2, v37 offset:296
	ds_write_b32 v2, v38 offset:560
	ds_write_b32 v2, v39 offset:824
	ds_write_b32 v2, v40 offset:64
	ds_write_b32 v2, v41 offset:328
	ds_write_b32 v2, v42 offset:592
	ds_write_b32 v2, v43 offset:856
	ds_write_b32 v2, v44 offset:96
	ds_write_b32 v2, v45 offset:360
	ds_write_b32 v2, v46 offset:624
	ds_write_b32 v2, v47 offset:888
	ds_write_b32 v2, v48 offset:128
	ds_write_b32 v2, v49 offset:392
	ds_write_b32 v2, v50 offset:656
	ds_write_b32 v2, v51 offset:920
	ds_write_b32 v2, v52 offset:160
	ds_write_b32 v2, v53 offset:424
	ds_write_b32 v2, v54 offset:688
	ds_write_b32 v2, v55 offset:952
	ds_write_b32 v2, v56 offset:192
	ds_write_b32 v2, v57 offset:456
	ds_write_b32 v2, v58 offset:720
	ds_write_b32 v2, v59 offset:984
	ds_write_b32 v2, v60 offset:224
	ds_write_b32 v2, v61 offset:488
	ds_write_b32 v2, v62 offset:752
	ds_write_b32 v2, v63 offset:1016
	s_lshr_b32 s70, s5, 2
	s_lshl_b32 s70, s70, 8
	s_and_b32 s71, s5, 3
	s_lshl_b32 s71, s71, 5
	s_add_i32 s70, s70, s71
	s_add_i32 s70, s70, s54
	s_lshl_b32 s70, s70, 12
	s_lshl_b32 s71, s4, 7
	s_add_i32 s70, s70, s71
	s_add_u32 s70, s70, 0x2200000
	s_add_u32 s70, s26, s70
	s_addc_u32 s71, s27, 0
	s_waitcnt lgkmcnt(0)
	ds_read_b64 v[160:161], v3 offset:0
	ds_read_b64 v[162:163], v3 offset:8
	ds_read_b64 v[164:165], v3 offset:16
	ds_read_b64 v[166:167], v3 offset:24
	ds_read_b64 v[168:169], v3 offset:2112
	ds_read_b64 v[170:171], v3 offset:2120
	ds_read_b64 v[172:173], v3 offset:2128
	ds_read_b64 v[174:175], v3 offset:2136
	ds_read_b64 v[176:177], v3 offset:4224
	ds_read_b64 v[178:179], v3 offset:4232
	ds_read_b64 v[180:181], v3 offset:4240
	ds_read_b64 v[182:183], v3 offset:4248
	ds_read_b64 v[184:185], v3 offset:6336
	ds_read_b64 v[186:187], v3 offset:6344
	ds_read_b64 v[188:189], v3 offset:6352
	ds_read_b64 v[190:191], v3 offset:6360
	s_waitcnt lgkmcnt(12)
	v_mul_f32_e32 v160, v160, v96
	v_mul_f32_e32 v161, v161, v97
	v_mul_f32_e32 v162, v162, v98
	v_mul_f32_e32 v163, v163, v99
	v_mul_f32_e32 v164, v164, v100
	v_mul_f32_e32 v165, v165, v101
	v_mul_f32_e32 v166, v166, v102
	v_mul_f32_e32 v167, v167, v103
	v_cvt_pk_bf16_f32 v192, v160, v161
	v_cvt_pk_bf16_f32 v193, v162, v163
	v_cvt_pk_bf16_f32 v194, v164, v165
	v_cvt_pk_bf16_f32 v195, v166, v167
	v_mov_b32_e32 v9, v4
	global_store_dwordx4 v9, v[192:195], s[70:71]
	s_waitcnt lgkmcnt(8)
	v_mul_f32_e32 v168, v168, v96
	v_mul_f32_e32 v169, v169, v97
	v_mul_f32_e32 v170, v170, v98
	v_mul_f32_e32 v171, v171, v99
	v_mul_f32_e32 v172, v172, v100
	v_mul_f32_e32 v173, v173, v101
	v_mul_f32_e32 v174, v174, v102
	v_mul_f32_e32 v175, v175, v103
	v_cvt_pk_bf16_f32 v196, v168, v169
	v_cvt_pk_bf16_f32 v197, v170, v171
	v_cvt_pk_bf16_f32 v198, v172, v173
	v_cvt_pk_bf16_f32 v199, v174, v175
	v_add_u32_e32 v9, 0x8000, v9
	global_store_dwordx4 v9, v[196:199], s[70:71]
	s_waitcnt lgkmcnt(4)
	v_mul_f32_e32 v176, v176, v96
	v_mul_f32_e32 v177, v177, v97
	v_mul_f32_e32 v178, v178, v98
	v_mul_f32_e32 v179, v179, v99
	v_mul_f32_e32 v180, v180, v100
	v_mul_f32_e32 v181, v181, v101
	v_mul_f32_e32 v182, v182, v102
	v_mul_f32_e32 v183, v183, v103
	v_cvt_pk_bf16_f32 v200, v176, v177
	v_cvt_pk_bf16_f32 v201, v178, v179
	v_cvt_pk_bf16_f32 v202, v180, v181
	v_cvt_pk_bf16_f32 v203, v182, v183
	v_add_u32_e32 v9, 0x8000, v9
	global_store_dwordx4 v9, v[200:203], s[70:71]
	s_waitcnt lgkmcnt(0)
	v_mul_f32_e32 v184, v184, v96
	v_mul_f32_e32 v185, v185, v97
	v_mul_f32_e32 v186, v186, v98
	v_mul_f32_e32 v187, v187, v99
	v_mul_f32_e32 v188, v188, v100
	v_mul_f32_e32 v189, v189, v101
	v_mul_f32_e32 v190, v190, v102
	v_mul_f32_e32 v191, v191, v103
	v_cvt_pk_bf16_f32 v204, v184, v185
	v_cvt_pk_bf16_f32 v205, v186, v187
	v_cvt_pk_bf16_f32 v206, v188, v189
	v_cvt_pk_bf16_f32 v207, v190, v191
	v_add_u32_e32 v9, 0x8000, v9
	global_store_dwordx4 v9, v[204:207], s[70:71]
	s_waitcnt vmcnt(0)
	s_waitcnt lgkmcnt(0)
	ds_write_b32 v2, v64 offset:0
	ds_write_b32 v2, v65 offset:264
	ds_write_b32 v2, v66 offset:528
	ds_write_b32 v2, v67 offset:792
	ds_write_b32 v2, v68 offset:32
	ds_write_b32 v2, v69 offset:296
	ds_write_b32 v2, v70 offset:560
	ds_write_b32 v2, v71 offset:824
	ds_write_b32 v2, v72 offset:64
	ds_write_b32 v2, v73 offset:328
	ds_write_b32 v2, v74 offset:592
	ds_write_b32 v2, v75 offset:856
	ds_write_b32 v2, v76 offset:96
	ds_write_b32 v2, v77 offset:360
	ds_write_b32 v2, v78 offset:624
	ds_write_b32 v2, v79 offset:888
	ds_write_b32 v2, v80 offset:128
	ds_write_b32 v2, v81 offset:392
	ds_write_b32 v2, v82 offset:656
	ds_write_b32 v2, v83 offset:920
	ds_write_b32 v2, v84 offset:160
	ds_write_b32 v2, v85 offset:424
	ds_write_b32 v2, v86 offset:688
	ds_write_b32 v2, v87 offset:952
	ds_write_b32 v2, v88 offset:192
	ds_write_b32 v2, v89 offset:456
	ds_write_b32 v2, v90 offset:720
	ds_write_b32 v2, v91 offset:984
	ds_write_b32 v2, v92 offset:224
	ds_write_b32 v2, v93 offset:488
	ds_write_b32 v2, v94 offset:752
	ds_write_b32 v2, v95 offset:1016
	s_lshr_b32 s70, s67, 2
	s_lshl_b32 s70, s70, 8
	s_and_b32 s71, s67, 3
	s_lshl_b32 s71, s71, 5
	s_add_i32 s70, s70, s71
	s_add_i32 s70, s70, s40
	s_lshl_b32 s70, s70, 12
	s_lshl_b32 s71, s55, 7
	s_add_i32 s70, s70, s71
	s_add_u32 s70, s70, 0x2200000
	s_add_u32 s70, s26, s70
	s_addc_u32 s71, s27, 0
	s_waitcnt lgkmcnt(0)
	ds_read_b64 v[160:161], v3 offset:0
	ds_read_b64 v[162:163], v3 offset:8
	ds_read_b64 v[164:165], v3 offset:16
	ds_read_b64 v[166:167], v3 offset:24
	ds_read_b64 v[168:169], v3 offset:2112
	ds_read_b64 v[170:171], v3 offset:2120
	ds_read_b64 v[172:173], v3 offset:2128
	ds_read_b64 v[174:175], v3 offset:2136
	ds_read_b64 v[176:177], v3 offset:4224
	ds_read_b64 v[178:179], v3 offset:4232
	ds_read_b64 v[180:181], v3 offset:4240
	ds_read_b64 v[182:183], v3 offset:4248
	ds_read_b64 v[184:185], v3 offset:6336
	ds_read_b64 v[186:187], v3 offset:6344
	ds_read_b64 v[188:189], v3 offset:6352
	ds_read_b64 v[190:191], v3 offset:6360
	s_waitcnt lgkmcnt(12)
	v_mul_f32_e32 v160, v160, v104
	v_mul_f32_e32 v161, v161, v105
	v_mul_f32_e32 v162, v162, v106
	v_mul_f32_e32 v163, v163, v107
	v_mul_f32_e32 v164, v164, v108
	v_mul_f32_e32 v165, v165, v109
	v_mul_f32_e32 v166, v166, v110
	v_mul_f32_e32 v167, v167, v111
	v_cvt_pk_bf16_f32 v192, v160, v161
	v_cvt_pk_bf16_f32 v193, v162, v163
	v_cvt_pk_bf16_f32 v194, v164, v165
	v_cvt_pk_bf16_f32 v195, v166, v167
	v_mov_b32_e32 v9, v4
	global_store_dwordx4 v9, v[192:195], s[70:71]
	s_waitcnt lgkmcnt(8)
	v_mul_f32_e32 v168, v168, v104
	v_mul_f32_e32 v169, v169, v105
	v_mul_f32_e32 v170, v170, v106
	v_mul_f32_e32 v171, v171, v107
	v_mul_f32_e32 v172, v172, v108
	v_mul_f32_e32 v173, v173, v109
	v_mul_f32_e32 v174, v174, v110
	v_mul_f32_e32 v175, v175, v111
	v_cvt_pk_bf16_f32 v196, v168, v169
	v_cvt_pk_bf16_f32 v197, v170, v171
	v_cvt_pk_bf16_f32 v198, v172, v173
	v_cvt_pk_bf16_f32 v199, v174, v175
	v_add_u32_e32 v9, 0x8000, v9
	global_store_dwordx4 v9, v[196:199], s[70:71]
	s_waitcnt lgkmcnt(4)
	v_mul_f32_e32 v176, v176, v104
	v_mul_f32_e32 v177, v177, v105
	v_mul_f32_e32 v178, v178, v106
	v_mul_f32_e32 v179, v179, v107
	v_mul_f32_e32 v180, v180, v108
	v_mul_f32_e32 v181, v181, v109
	v_mul_f32_e32 v182, v182, v110
	v_mul_f32_e32 v183, v183, v111
	v_cvt_pk_bf16_f32 v200, v176, v177
	v_cvt_pk_bf16_f32 v201, v178, v179
	v_cvt_pk_bf16_f32 v202, v180, v181
	v_cvt_pk_bf16_f32 v203, v182, v183
	v_add_u32_e32 v9, 0x8000, v9
	global_store_dwordx4 v9, v[200:203], s[70:71]
	s_waitcnt lgkmcnt(0)
	v_mul_f32_e32 v184, v184, v104
	v_mul_f32_e32 v185, v185, v105
	v_mul_f32_e32 v186, v186, v106
	v_mul_f32_e32 v187, v187, v107
	v_mul_f32_e32 v188, v188, v108
	v_mul_f32_e32 v189, v189, v109
	v_mul_f32_e32 v190, v190, v110
	v_mul_f32_e32 v191, v191, v111
	v_cvt_pk_bf16_f32 v204, v184, v185
	v_cvt_pk_bf16_f32 v205, v186, v187
	v_cvt_pk_bf16_f32 v206, v188, v189
	v_cvt_pk_bf16_f32 v207, v190, v191
	v_add_u32_e32 v9, 0x8000, v9
	global_store_dwordx4 v9, v[204:207], s[70:71]
	s_waitcnt vmcnt(0) lgkmcnt(0)

.LBB0_340:
	s_cmp_gt_u32 s29, 2
	s_cselect_b64 s[0:1], -1, 0
	s_and_b64 s[0:1], s[20:21], s[0:1]
	s_andn2_b64 vcc, exec, s[0:1]
	s_cbranch_vccnz .LBB0_392
	s_waitcnt vmcnt(0)
	v_cmp_eq_u32_e32 vcc, 0, v208
	s_waitcnt vmcnt(0) lgkmcnt(0)
	s_barrier
	v_readfirstlane_b32 s3, v208
	s_nop 3
	s_lshr_b32 s3, s3, 6
	s_cmp_eq_u32 s3, 0
	s_cbranch_scc1 .Lmy_cv1_end
	v_readlane_b32 s36, v237, 0
	v_readlane_b32 s37, v237, 1
	s_mul_i32 s4, s2, 7
	s_add_i32 s4, s4, s3
	s_add_i32 s4, s4, -1
	s_lshl_b32 s72, s3, 14
	s_mov_b32 s3, s4
	s_nop 4
	s_load_dwordx4 s[60:63], s[36:37], 0x60
	s_load_dwordx2 s[64:65], s[36:37], 0x70
	s_load_dwordx2 s[98:99], s[36:37], 0x58
	s_load_dwordx2 s[100:101], s[36:37], 0x48
	v_and_b32_e32 v8, 7, v209
	v_lshrrev_b32_e32 v9, 3, v209
	v_mul_u32_u24_e32 v0, 0x5800, v9
	v_lshl_add_u32 v0, v8, 4, v0
	v_lshlrev_b32_e32 v152, 13, v9
	v_lshl_add_u32 v152, v8, 4, v152
	v_mul_u32_u24_e32 v2, 0x420, v8
	v_lshl_add_u32 v2, v9, 2, v2
	v_add_u32_e32 v2, s72, v2
	v_mul_u32_u24_e32 v3, 0x108, v9
	v_lshl_add_u32 v3, v8, 5, v3
	v_add_u32_e32 v3, s72, v3
	v_lshlrev_b32_e32 v4, 12, v9
	v_lshl_add_u32 v4, v8, 4, v4
	v_lshlrev_b32_e32 v5, 5, v8
	s_waitcnt lgkmcnt(0)
	s_cmpk_lt_u32 s3, 0x200
	s_cbranch_scc0 .Lmy_cv1_no3a
	s_mov_b32 s66, s3
	s_cmpk_ge_u32 s66, 0x1600
	s_cselect_b32 s68, s64, s62
	s_cselect_b32 s69, s65, s63
	s_cselect_b32 s41, 0x1600, 0
	s_sub_u32 s41, s66, s41
	s_mul_hi_u32 vcc_lo, s41, 0xba2e8ba3
	s_lshr_b32 vcc_lo, vcc_lo, 7
	s_mul_i32 s70, vcc_lo, 0xb0
	s_sub_u32 vcc_hi, s41, s70
	s_mul_i32 s70, vcc_lo, 0x160000
	s_lshl_b32 s71, vcc_hi, 7
	s_add_u32 s68, s68, s70
	s_addc_u32 s69, s69, 0
	s_add_u32 s68, s68, s71
	s_addc_u32 s69, s69, 0
	v_mov_b32_e32 v1, v0
	global_load_dwordx4 v[112:115], v1, s[68:69] nt
	v_add_u32_e32 v1, 0x2c000, v1
	global_load_dwordx4 v[116:119], v1, s[68:69] nt
	v_add_u32_e32 v1, 0x2c000, v1
	global_load_dwordx4 v[120:123], v1, s[68:69] nt
	v_add_u32_e32 v1, 0x2c000, v1
	global_load_dwordx4 v[124:127], v1, s[68:69] nt
	v_add_u32_e32 v1, 0x2c000, v1
	global_load_dwordx4 v[128:131], v1, s[68:69] nt
	v_add_u32_e32 v1, 0x2c000, v1
	global_load_dwordx4 v[132:135], v1, s[68:69] nt
	v_add_u32_e32 v1, 0x2c000, v1
	global_load_dwordx4 v[136:139], v1, s[68:69] nt
	v_add_u32_e32 v1, 0x2c000, v1
	global_load_dwordx4 v[140:143], v1, s[68:69] nt
	s_lshl_b32 s70, vcc_lo, 8
	s_add_u32 s70, s60, s70
	s_addc_u32 s71, s61, 0
	global_load_dwordx4 v[144:147], v5, s[70:71]
	global_load_dwordx4 v[148:151], v5, s[70:71] offset:16
	s_branch .Lmy_cv1_dn3a
.Lmy_cv1_no3a:
	s_cmpk_lt_u32 s3, 0x300
	s_cbranch_scc0 .Lmy_cv1_dn3a
	s_add_i32 s66, s3, 0xfffffe00
	s_lshr_b32 vcc_lo, s66, 6
	s_and_b32 vcc_hi, s66, 63
	s_lshl_b32 s70, vcc_lo, 19
	s_lshl_b32 s71, vcc_hi, 7
	s_add_u32 s68, s98, s70
	s_addc_u32 s69, s99, 0
	s_add_u32 s68, s68, s71
	s_addc_u32 s69, s69, 0
	v_mov_b32_e32 v1, v152
	global_load_dwordx4 v[112:115], v1, s[68:69] nt
	v_add_u32_e32 v1, 0x10000, v1
	global_load_dwordx4 v[116:119], v1, s[68:69] nt
	v_add_u32_e32 v1, 0x10000, v1
	global_load_dwordx4 v[120:123], v1, s[68:69] nt
	v_add_u32_e32 v1, 0x10000, v1
	global_load_dwordx4 v[124:127], v1, s[68:69] nt
	v_add_u32_e32 v1, 0x10000, v1
	global_load_dwordx4 v[128:131], v1, s[68:69] nt
	v_add_u32_e32 v1, 0x10000, v1
	global_load_dwordx4 v[132:135], v1, s[68:69] nt
	v_add_u32_e32 v1, 0x10000, v1
	global_load_dwordx4 v[136:139], v1, s[68:69] nt
	v_add_u32_e32 v1, 0x10000, v1
	global_load_dwordx4 v[140:143], v1, s[68:69] nt
	s_and_b32 s70, vcc_lo, 1
	s_lshl_b32 s70, s70, 8
	s_add_u32 s70, s100, s70
	s_addc_u32 s71, s101, 0
	global_load_dwordx4 v[144:147], v5, s[70:71]
	global_load_dwordx4 v[148:151], v5, s[70:71] offset:16
.Lmy_cv1_dn3a:
	s_add_i32 s66, s3, 4096
	s_cmpk_ge_u32 s66, 0x1600
	s_cselect_b32 s68, s64, s62
	s_cselect_b32 s69, s65, s63
	s_cselect_b32 s54, 128, 0
	s_cselect_b32 s41, 0x1600, 0
	s_sub_u32 s41, s66, s41
	s_mul_hi_u32 s4, s41, 0xba2e8ba3
	s_lshr_b32 s4, s4, 7
	s_mul_i32 s70, s4, 0xb0
	s_sub_u32 s5, s41, s70
	s_mul_i32 s70, s4, 0x160000
	s_lshl_b32 s71, s5, 7
	s_add_u32 s68, s68, s70
	s_addc_u32 s69, s69, 0
	s_add_u32 s68, s68, s71
	s_addc_u32 s69, s69, 0
	v_mov_b32_e32 v1, v0
	global_load_dwordx4 v[32:35], v1, s[68:69] nt
	v_add_u32_e32 v1, 0x2c000, v1
	global_load_dwordx4 v[36:39], v1, s[68:69] nt
	v_add_u32_e32 v1, 0x2c000, v1
	global_load_dwordx4 v[40:43], v1, s[68:69] nt
	v_add_u32_e32 v1, 0x2c000, v1
	global_load_dwordx4 v[44:47], v1, s[68:69] nt
	v_add_u32_e32 v1, 0x2c000, v1
	global_load_dwordx4 v[48:51], v1, s[68:69] nt
	v_add_u32_e32 v1, 0x2c000, v1
	global_load_dwordx4 v[52:55], v1, s[68:69] nt
	v_add_u32_e32 v1, 0x2c000, v1
	global_load_dwordx4 v[56:59], v1, s[68:69] nt
	v_add_u32_e32 v1, 0x2c000, v1
	global_load_dwordx4 v[60:63], v1, s[68:69] nt
	s_lshl_b32 s70, s4, 8
	s_add_u32 s70, s60, s70
	s_addc_u32 s71, s61, 0
	global_load_dwordx4 v[96:99], v5, s[70:71]
	global_load_dwordx4 v[100:103], v5, s[70:71] offset:16
	s_addk_i32 s66, 0x700
	s_cmpk_ge_u32 s66, 0x1600
	s_cselect_b32 s68, s64, s62
	s_cselect_b32 s69, s65, s63
	s_cselect_b32 s40, 128, 0
	s_cselect_b32 s41, 0x1600, 0
	s_sub_u32 s41, s66, s41
	s_mul_hi_u32 s55, s41, 0xba2e8ba3
	s_lshr_b32 s55, s55, 7
	s_mul_i32 s70, s55, 0xb0
	s_sub_u32 s67, s41, s70
	s_mul_i32 s70, s55, 0x160000
	s_lshl_b32 s71, s67, 7
	s_add_u32 s68, s68, s70
	s_addc_u32 s69, s69, 0
	s_add_u32 s68, s68, s71
	s_addc_u32 s69, s69, 0
	v_mov_b32_e32 v1, v0
	global_load_dwordx4 v[64:67], v1, s[68:69] nt
	v_add_u32_e32 v1, 0x2c000, v1
	global_load_dwordx4 v[68:71], v1, s[68:69] nt
	v_add_u32_e32 v1, 0x2c000, v1
	global_load_dwordx4 v[72:75], v1, s[68:69] nt
	v_add_u32_e32 v1, 0x2c000, v1
	global_load_dwordx4 v[76:79], v1, s[68:69] nt
	v_add_u32_e32 v1, 0x2c000, v1
	global_load_dwordx4 v[80:83], v1, s[68:69] nt
	v_add_u32_e32 v1, 0x2c000, v1
	global_load_dwordx4 v[84:87], v1, s[68:69] nt
	v_add_u32_e32 v1, 0x2c000, v1
	global_load_dwordx4 v[88:91], v1, s[68:69] nt
	v_add_u32_e32 v1, 0x2c000, v1
	global_load_dwordx4 v[92:95], v1, s[68:69] nt
	s_lshl_b32 s70, s55, 8
	s_add_u32 s70, s60, s70
	s_addc_u32 s71, s61, 0
	global_load_dwordx4 v[104:107], v5, s[70:71]
	global_load_dwordx4 v[108:111], v5, s[70:71] offset:16
	s_cmpk_lt_u32 s3, 0x200
	s_cbranch_scc0 .Lmy_cv1_no3b
	s_waitcnt vmcnt(20)
	s_waitcnt lgkmcnt(0)
	ds_write_b32 v2, v112 offset:0
	ds_write_b32 v2, v113 offset:264
	ds_write_b32 v2, v114 offset:528
	ds_write_b32 v2, v115 offset:792
	ds_write_b32 v2, v116 offset:32
	ds_write_b32 v2, v117 offset:296
	ds_write_b32 v2, v118 offset:560
	ds_write_b32 v2, v119 offset:824
	ds_write_b32 v2, v120 offset:64
	ds_write_b32 v2, v121 offset:328
	ds_write_b32 v2, v122 offset:592
	ds_write_b32 v2, v123 offset:856
	ds_write_b32 v2, v124 offset:96
	ds_write_b32 v2, v125 offset:360
	ds_write_b32 v2, v126 offset:624
	ds_write_b32 v2, v127 offset:888
	ds_write_b32 v2, v128 offset:128
	ds_write_b32 v2, v129 offset:392
	ds_write_b32 v2, v130 offset:656
	ds_write_b32 v2, v131 offset:920
	ds_write_b32 v2, v132 offset:160
	ds_write_b32 v2, v133 offset:424
	ds_write_b32 v2, v134 offset:688
	ds_write_b32 v2, v135 offset:952
	ds_write_b32 v2, v136 offset:192
	ds_write_b32 v2, v137 offset:456
	ds_write_b32 v2, v138 offset:720
	ds_write_b32 v2, v139 offset:984
	ds_write_b32 v2, v140 offset:224
	ds_write_b32 v2, v141 offset:488
	ds_write_b32 v2, v142 offset:752
	ds_write_b32 v2, v143 offset:1016
	s_lshr_b32 s70, vcc_hi, 2
	s_lshl_b32 s70, s70, 8
	s_and_b32 s71, vcc_hi, 3
	s_lshl_b32 s71, s71, 5
	s_add_i32 s70, s70, s71
	s_lshl_b32 s70, s70, 12
	s_lshl_b32 s71, vcc_lo, 7
	s_add_i32 s70, s70, s71
	s_add_u32 s70, s70, 0x2200000
	s_add_u32 s70, s26, s70
	s_addc_u32 s71, s27, 0
	s_waitcnt lgkmcnt(0)
	ds_read_b64 v[160:161], v3 offset:0
	ds_read_b64 v[162:163], v3 offset:8
	ds_read_b64 v[164:165], v3 offset:16
	ds_read_b64 v[166:167], v3 offset:24
	ds_read_b64 v[168:169], v3 offset:2112
	ds_read_b64 v[170:171], v3 offset:2120
	ds_read_b64 v[172:173], v3 offset:2128
	ds_read_b64 v[174:175], v3 offset:2136
	ds_read_b64 v[176:177], v3 offset:4224
	ds_read_b64 v[178:179], v3 offset:4232
	ds_read_b64 v[180:181], v3 offset:4240
	ds_read_b64 v[182:183], v3 offset:4248
	ds_read_b64 v[184:185], v3 offset:6336
	ds_read_b64 v[186:187], v3 offset:6344
	ds_read_b64 v[188:189], v3 offset:6352
	ds_read_b64 v[190:191], v3 offset:6360
	s_waitcnt lgkmcnt(12)
	v_mul_f32_e32 v160, v160, v144
	v_mul_f32_e32 v161, v161, v145
	v_mul_f32_e32 v162, v162, v146
	v_mul_f32_e32 v163, v163, v147
	v_mul_f32_e32 v164, v164, v148
	v_mul_f32_e32 v165, v165, v149
	v_mul_f32_e32 v166, v166, v150
	v_mul_f32_e32 v167, v167, v151
	v_cvt_pk_bf16_f32 v192, v160, v161
	v_cvt_pk_bf16_f32 v193, v162, v163
	v_cvt_pk_bf16_f32 v194, v164, v165
	v_cvt_pk_bf16_f32 v195, v166, v167
	v_mov_b32_e32 v9, v4
	global_store_dwordx4 v9, v[192:195], s[70:71]
	s_waitcnt lgkmcnt(8)
	v_mul_f32_e32 v168, v168, v144
	v_mul_f32_e32 v169, v169, v145
	v_mul_f32_e32 v170, v170, v146
	v_mul_f32_e32 v171, v171, v147
	v_mul_f32_e32 v172, v172, v148
	v_mul_f32_e32 v173, v173, v149
	v_mul_f32_e32 v174, v174, v150
	v_mul_f32_e32 v175, v175, v151
	v_cvt_pk_bf16_f32 v196, v168, v169
	v_cvt_pk_bf16_f32 v197, v170, v171
	v_cvt_pk_bf16_f32 v198, v172, v173
	v_cvt_pk_bf16_f32 v199, v174, v175
	v_add_u32_e32 v9, 0x8000, v9
	global_store_dwordx4 v9, v[196:199], s[70:71]
	s_waitcnt lgkmcnt(4)
	v_mul_f32_e32 v176, v176, v144
	v_mul_f32_e32 v177, v177, v145
	v_mul_f32_e32 v178, v178, v146
	v_mul_f32_e32 v179, v179, v147
	v_mul_f32_e32 v180, v180, v148
	v_mul_f32_e32 v181, v181, v149
	v_mul_f32_e32 v182, v182, v150
	v_mul_f32_e32 v183, v183, v151
	v_cvt_pk_bf16_f32 v200, v176, v177
	v_cvt_pk_bf16_f32 v201, v178, v179
	v_cvt_pk_bf16_f32 v202, v180, v181
	v_cvt_pk_bf16_f32 v203, v182, v183
	v_add_u32_e32 v9, 0x8000, v9
	global_store_dwordx4 v9, v[200:203], s[70:71]
	s_waitcnt lgkmcnt(0)
	v_mul_f32_e32 v184, v184, v144
	v_mul_f32_e32 v185, v185, v145
	v_mul_f32_e32 v186, v186, v146
	v_mul_f32_e32 v187, v187, v147
	v_mul_f32_e32 v188, v188, v148
	v_mul_f32_e32 v189, v189, v149
	v_mul_f32_e32 v190, v190, v150
	v_mul_f32_e32 v191, v191, v151
	v_cvt_pk_bf16_f32 v204, v184, v185
	v_cvt_pk_bf16_f32 v205, v186, v187
	v_cvt_pk_bf16_f32 v206, v188, v189
	v_cvt_pk_bf16_f32 v207, v190, v191
	v_add_u32_e32 v9, 0x8000, v9
	global_store_dwordx4 v9, v[204:207], s[70:71]
	s_branch .Lmy_cv1_dn3b
.Lmy_cv1_no3b:
	s_cmpk_lt_u32 s3, 0x300
	s_cbranch_scc0 .Lmy_cv1_dn3b
	s_waitcnt vmcnt(20)
	s_waitcnt lgkmcnt(0)
	ds_write_b32 v2, v112 offset:0
	ds_write_b32 v2, v113 offset:264
	ds_write_b32 v2, v114 offset:528
	ds_write_b32 v2, v115 offset:792
	ds_write_b32 v2, v116 offset:32
	ds_write_b32 v2, v117 offset:296
	ds_write_b32 v2, v118 offset:560
	ds_write_b32 v2, v119 offset:824
	ds_write_b32 v2, v120 offset:64
	ds_write_b32 v2, v121 offset:328
	ds_write_b32 v2, v122 offset:592
	ds_write_b32 v2, v123 offset:856
	ds_write_b32 v2, v124 offset:96
	ds_write_b32 v2, v125 offset:360
	ds_write_b32 v2, v126 offset:624
	ds_write_b32 v2, v127 offset:888
	ds_write_b32 v2, v128 offset:128
	ds_write_b32 v2, v129 offset:392
	ds_write_b32 v2, v130 offset:656
	ds_write_b32 v2, v131 offset:920
	ds_write_b32 v2, v132 offset:160
	ds_write_b32 v2, v133 offset:424
	ds_write_b32 v2, v134 offset:688
	ds_write_b32 v2, v135 offset:952
	ds_write_b32 v2, v136 offset:192
	ds_write_b32 v2, v137 offset:456
	ds_write_b32 v2, v138 offset:720
	ds_write_b32 v2, v139 offset:984
	ds_write_b32 v2, v140 offset:224
	ds_write_b32 v2, v141 offset:488
	ds_write_b32 v2, v142 offset:752
	ds_write_b32 v2, v143 offset:1016
	s_cmp_lt_u32 vcc_lo, 16
	s_cbranch_scc0 .Lmy_cv1_nsx
	v_mul_f32_e32 v144, 0x3f4ccccd, v144
	v_mul_f32_e32 v145, 0x3f4ccccd, v145
	v_mul_f32_e32 v146, 0x3f4ccccd, v146
	v_mul_f32_e32 v147, 0x3f4ccccd, v147
	v_mul_f32_e32 v148, 0x3f4ccccd, v148
	v_mul_f32_e32 v149, 0x3f4ccccd, v149
	v_mul_f32_e32 v150, 0x3f4ccccd, v150
	v_mul_f32_e32 v151, 0x3f4ccccd, v151
	s_branch .Lmy_cv1_sdx

.Lmy_cv1_dn3b:
	s_waitcnt vmcnt(10)
	s_waitcnt lgkmcnt(0)
	ds_write_b32 v2, v32 offset:0
	ds_write_b32 v2, v33 offset:264
	ds_write_b32 v2, v34 offset:528
	ds_write_b32 v2, v35 offset:792
	ds_write_b32 v2, v36 offset:32
	ds_write_b32 v2, v37 offset:296
	ds_write_b32 v2, v38 offset:560
	ds_write_b32 v2, v39 offset:824
	ds_write_b32 v2, v40 offset:64
	ds_write_b32 v2, v41 offset:328
	ds_write_b32 v2, v42 offset:592
	ds_write_b32 v2, v43 offset:856
	ds_write_b32 v2, v44 offset:96
	ds_write_b32 v2, v45 offset:360
	ds_write_b32 v2, v46 offset:624
	ds_write_b32 v2, v47 offset:888
	ds_write_b32 v2, v48 offset:128
	ds_write_b32 v2, v49 offset:392
	ds_write_b32 v2, v50 offset:656
	ds_write_b32 v2, v51 offset:920
	ds_write_b32 v2, v52 offset:160
	ds_write_b32 v2, v53 offset:424
	ds_write_b32 v2, v54 offset:688
	ds_write_b32 v2, v55 offset:952
	ds_write_b32 v2, v56 offset:192
	ds_write_b32 v2, v57 offset:456
	ds_write_b32 v2, v58 offset:720
	ds_write_b32 v2, v59 offset:984
	ds_write_b32 v2, v60 offset:224
	ds_write_b32 v2, v61 offset:488
	ds_write_b32 v2, v62 offset:752
	ds_write_b32 v2, v63 offset:1016
	s_lshr_b32 s70, s5, 2
	s_lshl_b32 s70, s70, 8
	s_and_b32 s71, s5, 3
	s_lshl_b32 s71, s71, 5
	s_add_i32 s70, s70, s71
	s_add_i32 s70, s70, s54
	s_lshl_b32 s70, s70, 12
	s_lshl_b32 s71, s4, 7
	s_add_i32 s70, s70, s71
	s_add_u32 s70, s70, 0x2200000
	s_add_u32 s70, s26, s70
	s_addc_u32 s71, s27, 0
	s_waitcnt lgkmcnt(0)
	ds_read_b64 v[160:161], v3 offset:0
	ds_read_b64 v[162:163], v3 offset:8
	ds_read_b64 v[164:165], v3 offset:16
	ds_read_b64 v[166:167], v3 offset:24
	ds_read_b64 v[168:169], v3 offset:2112
	ds_read_b64 v[170:171], v3 offset:2120
	ds_read_b64 v[172:173], v3 offset:2128
	ds_read_b64 v[174:175], v3 offset:2136
	ds_read_b64 v[176:177], v3 offset:4224
	ds_read_b64 v[178:179], v3 offset:4232
	ds_read_b64 v[180:181], v3 offset:4240
	ds_read_b64 v[182:183], v3 offset:4248
	ds_read_b64 v[184:185], v3 offset:6336
	ds_read_b64 v[186:187], v3 offset:6344
	ds_read_b64 v[188:189], v3 offset:6352
	ds_read_b64 v[190:191], v3 offset:6360
	s_waitcnt lgkmcnt(12)
	v_mul_f32_e32 v160, v160, v96
	v_mul_f32_e32 v161, v161, v97
	v_mul_f32_e32 v162, v162, v98
	v_mul_f32_e32 v163, v163, v99
	v_mul_f32_e32 v164, v164, v100
	v_mul_f32_e32 v165, v165, v101
	v_mul_f32_e32 v166, v166, v102
	v_mul_f32_e32 v167, v167, v103
	v_cvt_pk_bf16_f32 v192, v160, v161
	v_cvt_pk_bf16_f32 v193, v162, v163
	v_cvt_pk_bf16_f32 v194, v164, v165
	v_cvt_pk_bf16_f32 v195, v166, v167
	v_mov_b32_e32 v9, v4
	global_store_dwordx4 v9, v[192:195], s[70:71]
	s_waitcnt lgkmcnt(8)
	v_mul_f32_e32 v168, v168, v96
	v_mul_f32_e32 v169, v169, v97
	v_mul_f32_e32 v170, v170, v98
	v_mul_f32_e32 v171, v171, v99
	v_mul_f32_e32 v172, v172, v100
	v_mul_f32_e32 v173, v173, v101
	v_mul_f32_e32 v174, v174, v102
	v_mul_f32_e32 v175, v175, v103
	v_cvt_pk_bf16_f32 v196, v168, v169
	v_cvt_pk_bf16_f32 v197, v170, v171
	v_cvt_pk_bf16_f32 v198, v172, v173
	v_cvt_pk_bf16_f32 v199, v174, v175
	v_add_u32_e32 v9, 0x8000, v9
	global_store_dwordx4 v9, v[196:199], s[70:71]
	s_waitcnt lgkmcnt(4)
	v_mul_f32_e32 v176, v176, v96
	v_mul_f32_e32 v177, v177, v97
	v_mul_f32_e32 v178, v178, v98
	v_mul_f32_e32 v179, v179, v99
	v_mul_f32_e32 v180, v180, v100
	v_mul_f32_e32 v181, v181, v101
	v_mul_f32_e32 v182, v182, v102
	v_mul_f32_e32 v183, v183, v103
	v_cvt_pk_bf16_f32 v200, v176, v177
	v_cvt_pk_bf16_f32 v201, v178, v179
	v_cvt_pk_bf16_f32 v202, v180, v181
	v_cvt_pk_bf16_f32 v203, v182, v183
	v_add_u32_e32 v9, 0x8000, v9
	global_store_dwordx4 v9, v[200:203], s[70:71]
	s_waitcnt lgkmcnt(0)
	v_mul_f32_e32 v184, v184, v96
	v_mul_f32_e32 v185, v185, v97
	v_mul_f32_e32 v186, v186, v98
	v_mul_f32_e32 v187, v187, v99
	v_mul_f32_e32 v188, v188, v100
	v_mul_f32_e32 v189, v189, v101
	v_mul_f32_e32 v190, v190, v102
	v_mul_f32_e32 v191, v191, v103
	v_cvt_pk_bf16_f32 v204, v184, v185
	v_cvt_pk_bf16_f32 v205, v186, v187
	v_cvt_pk_bf16_f32 v206, v188, v189
	v_cvt_pk_bf16_f32 v207, v190, v191
	v_add_u32_e32 v9, 0x8000, v9
	global_store_dwordx4 v9, v[204:207], s[70:71]
	s_waitcnt vmcnt(0)
	s_waitcnt lgkmcnt(0)
	ds_write_b32 v2, v64 offset:0
	ds_write_b32 v2, v65 offset:264
	ds_write_b32 v2, v66 offset:528
	ds_write_b32 v2, v67 offset:792
	ds_write_b32 v2, v68 offset:32
	ds_write_b32 v2, v69 offset:296
	ds_write_b32 v2, v70 offset:560
	ds_write_b32 v2, v71 offset:824
	ds_write_b32 v2, v72 offset:64
	ds_write_b32 v2, v73 offset:328
	ds_write_b32 v2, v74 offset:592
	ds_write_b32 v2, v75 offset:856
	ds_write_b32 v2, v76 offset:96
	ds_write_b32 v2, v77 offset:360
	ds_write_b32 v2, v78 offset:624
	ds_write_b32 v2, v79 offset:888
	ds_write_b32 v2, v80 offset:128
	ds_write_b32 v2, v81 offset:392
	ds_write_b32 v2, v82 offset:656
	ds_write_b32 v2, v83 offset:920
	ds_write_b32 v2, v84 offset:160
	ds_write_b32 v2, v85 offset:424
	ds_write_b32 v2, v86 offset:688
	ds_write_b32 v2, v87 offset:952
	ds_write_b32 v2, v88 offset:192
	ds_write_b32 v2, v89 offset:456
	ds_write_b32 v2, v90 offset:720
	ds_write_b32 v2, v91 offset:984
	ds_write_b32 v2, v92 offset:224
	ds_write_b32 v2, v93 offset:488
	ds_write_b32 v2, v94 offset:752
	ds_write_b32 v2, v95 offset:1016
	s_lshr_b32 s70, s67, 2
	s_lshl_b32 s70, s70, 8
	s_and_b32 s71, s67, 3
	s_lshl_b32 s71, s71, 5
	s_add_i32 s70, s70, s71
	s_add_i32 s70, s70, s40
	s_lshl_b32 s70, s70, 12
	s_lshl_b32 s71, s55, 7
	s_add_i32 s70, s70, s71
	s_add_u32 s70, s70, 0x2200000
	s_add_u32 s70, s26, s70
	s_addc_u32 s71, s27, 0
	s_waitcnt lgkmcnt(0)
	ds_read_b64 v[160:161], v3 offset:0
	ds_read_b64 v[162:163], v3 offset:8
	ds_read_b64 v[164:165], v3 offset:16
	ds_read_b64 v[166:167], v3 offset:24
	ds_read_b64 v[168:169], v3 offset:2112
	ds_read_b64 v[170:171], v3 offset:2120
	ds_read_b64 v[172:173], v3 offset:2128
	ds_read_b64 v[174:175], v3 offset:2136
	ds_read_b64 v[176:177], v3 offset:4224
	ds_read_b64 v[178:179], v3 offset:4232
	ds_read_b64 v[180:181], v3 offset:4240
	ds_read_b64 v[182:183], v3 offset:4248
	ds_read_b64 v[184:185], v3 offset:6336
	ds_read_b64 v[186:187], v3 offset:6344
	ds_read_b64 v[188:189], v3 offset:6352
	ds_read_b64 v[190:191], v3 offset:6360
	s_waitcnt lgkmcnt(12)
	v_mul_f32_e32 v160, v160, v104
	v_mul_f32_e32 v161, v161, v105
	v_mul_f32_e32 v162, v162, v106
	v_mul_f32_e32 v163, v163, v107
	v_mul_f32_e32 v164, v164, v108
	v_mul_f32_e32 v165, v165, v109
	v_mul_f32_e32 v166, v166, v110
	v_mul_f32_e32 v167, v167, v111
	v_cvt_pk_bf16_f32 v192, v160, v161
	v_cvt_pk_bf16_f32 v193, v162, v163
	v_cvt_pk_bf16_f32 v194, v164, v165
	v_cvt_pk_bf16_f32 v195, v166, v167
	v_mov_b32_e32 v9, v4
	global_store_dwordx4 v9, v[192:195], s[70:71]
	s_waitcnt lgkmcnt(8)
	v_mul_f32_e32 v168, v168, v104
	v_mul_f32_e32 v169, v169, v105
	v_mul_f32_e32 v170, v170, v106
	v_mul_f32_e32 v171, v171, v107
	v_mul_f32_e32 v172, v172, v108
	v_mul_f32_e32 v173, v173, v109
	v_mul_f32_e32 v174, v174, v110
	v_mul_f32_e32 v175, v175, v111
	v_cvt_pk_bf16_f32 v196, v168, v169
	v_cvt_pk_bf16_f32 v197, v170, v171
	v_cvt_pk_bf16_f32 v198, v172, v173
	v_cvt_pk_bf16_f32 v199, v174, v175
	v_add_u32_e32 v9, 0x8000, v9
	global_store_dwordx4 v9, v[196:199], s[70:71]
	s_waitcnt lgkmcnt(4)
	v_mul_f32_e32 v176, v176, v104
	v_mul_f32_e32 v177, v177, v105
	v_mul_f32_e32 v178, v178, v106
	v_mul_f32_e32 v179, v179, v107
	v_mul_f32_e32 v180, v180, v108
	v_mul_f32_e32 v181, v181, v109
	v_mul_f32_e32 v182, v182, v110
	v_mul_f32_e32 v183, v183, v111
	v_cvt_pk_bf16_f32 v200, v176, v177
	v_cvt_pk_bf16_f32 v201, v178, v179
	v_cvt_pk_bf16_f32 v202, v180, v181
	v_cvt_pk_bf16_f32 v203, v182, v183
	v_add_u32_e32 v9, 0x8000, v9
	global_store_dwordx4 v9, v[200:203], s[70:71]
	s_waitcnt lgkmcnt(0)
	v_mul_f32_e32 v184, v184, v104
	v_mul_f32_e32 v185, v185, v105
	v_mul_f32_e32 v186, v186, v106
	v_mul_f32_e32 v187, v187, v107
	v_mul_f32_e32 v188, v188, v108
	v_mul_f32_e32 v189, v189, v109
	v_mul_f32_e32 v190, v190, v110
	v_mul_f32_e32 v191, v191, v111
	v_cvt_pk_bf16_f32 v204, v184, v185
	v_cvt_pk_bf16_f32 v205, v186, v187
	v_cvt_pk_bf16_f32 v206, v188, v189
	v_cvt_pk_bf16_f32 v207, v190, v191
	v_add_u32_e32 v9, 0x8000, v9
	global_store_dwordx4 v9, v[204:207], s[70:71]
	s_waitcnt vmcnt(0) lgkmcnt(0)

.LBB0_475:
	s_cmp_gt_u32 s29, 4
	s_cselect_b64 s[0:1], -1, 0
	s_and_b64 s[0:1], s[36:37], s[0:1]
	s_andn2_b64 vcc, exec, s[0:1]
	s_cbranch_vccnz .LBB0_525
	s_waitcnt vmcnt(0)
	v_cmp_eq_u32_e32 vcc, 0, v208
	s_waitcnt vmcnt(0) lgkmcnt(0)
	s_barrier
	v_readfirstlane_b32 s3, v208
	s_nop 3
	s_lshr_b32 s3, s3, 6
	s_cmp_eq_u32 s3, 0
	s_cbranch_scc1 .Lmy_cv2_end
	v_readlane_b32 s36, v237, 0
	v_readlane_b32 s37, v237, 1
	s_mul_i32 s4, s2, 7
	s_add_i32 s4, s4, s3
	s_add_i32 s4, s4, -1
	s_lshl_b32 s72, s3, 14
	s_mov_b32 s3, s4
	s_nop 4
	s_load_dwordx4 s[60:63], s[36:37], 0x60
	s_load_dwordx2 s[64:65], s[36:37], 0x70
	v_and_b32_e32 v8, 7, v209
	v_lshrrev_b32_e32 v9, 3, v209
	v_mul_u32_u24_e32 v0, 0x5800, v9
	v_lshl_add_u32 v0, v8, 4, v0
	v_lshlrev_b32_e32 v152, 13, v9
	v_lshl_add_u32 v152, v8, 4, v152
	v_mul_u32_u24_e32 v2, 0x420, v8
	v_lshl_add_u32 v2, v9, 2, v2
	v_add_u32_e32 v2, s72, v2
	v_mul_u32_u24_e32 v3, 0x108, v9
	v_lshl_add_u32 v3, v8, 5, v3
	v_add_u32_e32 v3, s72, v3
	v_lshlrev_b32_e32 v4, 12, v9
	v_lshl_add_u32 v4, v8, 4, v4
	v_lshlrev_b32_e32 v5, 5, v8
	s_waitcnt lgkmcnt(0)
	s_add_i32 s66, s3, 7680
	s_cmpk_ge_u32 s66, 0x1600
	s_cselect_b32 s68, s64, s62
	s_cselect_b32 s69, s65, s63
	s_cselect_b32 s54, 128, 0
	s_cselect_b32 s41, 0x1600, 0
	s_sub_u32 s41, s66, s41
	s_mul_hi_u32 s4, s41, 0xba2e8ba3
	s_lshr_b32 s4, s4, 7
	s_mul_i32 s70, s4, 0xb0
	s_sub_u32 s5, s41, s70
	s_mul_i32 s70, s4, 0x160000
	s_lshl_b32 s71, s5, 7
	s_add_u32 s68, s68, s70
	s_addc_u32 s69, s69, 0
	s_add_u32 s68, s68, s71
	s_addc_u32 s69, s69, 0
	v_mov_b32_e32 v1, v0
	global_load_dwordx4 v[32:35], v1, s[68:69] nt
	v_add_u32_e32 v1, 0x2c000, v1
	global_load_dwordx4 v[36:39], v1, s[68:69] nt
	v_add_u32_e32 v1, 0x2c000, v1
	global_load_dwordx4 v[40:43], v1, s[68:69] nt
	v_add_u32_e32 v1, 0x2c000, v1
	global_load_dwordx4 v[44:47], v1, s[68:69] nt
	v_add_u32_e32 v1, 0x2c000, v1
	global_load_dwordx4 v[48:51], v1, s[68:69] nt
	v_add_u32_e32 v1, 0x2c000, v1
	global_load_dwordx4 v[52:55], v1, s[68:69] nt
	v_add_u32_e32 v1, 0x2c000, v1
	global_load_dwordx4 v[56:59], v1, s[68:69] nt
	v_add_u32_e32 v1, 0x2c000, v1
	global_load_dwordx4 v[60:63], v1, s[68:69] nt
	s_lshl_b32 s70, s4, 8
	s_add_u32 s70, s60, s70
	s_addc_u32 s71, s61, 0
	global_load_dwordx4 v[96:99], v5, s[70:71]
	global_load_dwordx4 v[100:103], v5, s[70:71] offset:16
	s_addk_i32 s66, 0x700
	s_cmpk_ge_u32 s66, 0x1600
	s_cselect_b32 s68, s64, s62
	s_cselect_b32 s69, s65, s63
	s_cselect_b32 s40, 128, 0
	s_cselect_b32 s41, 0x1600, 0
	s_sub_u32 s41, s66, s41
	s_mul_hi_u32 s55, s41, 0xba2e8ba3
	s_lshr_b32 s55, s55, 7
	s_mul_i32 s70, s55, 0xb0
	s_sub_u32 s67, s41, s70
	s_mul_i32 s70, s55, 0x160000
	s_lshl_b32 s71, s67, 7
	s_add_u32 s68, s68, s70
	s_addc_u32 s69, s69, 0
	s_add_u32 s68, s68, s71
	s_addc_u32 s69, s69, 0
	v_mov_b32_e32 v1, v0
	global_load_dwordx4 v[64:67], v1, s[68:69] nt
	v_add_u32_e32 v1, 0x2c000, v1
	global_load_dwordx4 v[68:71], v1, s[68:69] nt
	v_add_u32_e32 v1, 0x2c000, v1
	global_load_dwordx4 v[72:75], v1, s[68:69] nt
	v_add_u32_e32 v1, 0x2c000, v1
	global_load_dwordx4 v[76:79], v1, s[68:69] nt
	v_add_u32_e32 v1, 0x2c000, v1
	global_load_dwordx4 v[80:83], v1, s[68:69] nt
	v_add_u32_e32 v1, 0x2c000, v1
	global_load_dwordx4 v[84:87], v1, s[68:69] nt
	v_add_u32_e32 v1, 0x2c000, v1
	global_load_dwordx4 v[88:91], v1, s[68:69] nt
	v_add_u32_e32 v1, 0x2c000, v1
	global_load_dwordx4 v[92:95], v1, s[68:69] nt
	s_lshl_b32 s70, s55, 8
	s_add_u32 s70, s60, s70
	s_addc_u32 s71, s61, 0
	global_load_dwordx4 v[104:107], v5, s[70:71]
	global_load_dwordx4 v[108:111], v5, s[70:71] offset:16
	s_waitcnt vmcnt(10)
	s_waitcnt lgkmcnt(0)
	ds_write_b32 v2, v32 offset:0
	ds_write_b32 v2, v33 offset:264
	ds_write_b32 v2, v34 offset:528
	ds_write_b32 v2, v35 offset:792
	ds_write_b32 v2, v36 offset:32
	ds_write_b32 v2, v37 offset:296
	ds_write_b32 v2, v38 offset:560
	ds_write_b32 v2, v39 offset:824
	ds_write_b32 v2, v40 offset:64
	ds_write_b32 v2, v41 offset:328
	ds_write_b32 v2, v42 offset:592
	ds_write_b32 v2, v43 offset:856
	ds_write_b32 v2, v44 offset:96
	ds_write_b32 v2, v45 offset:360
	ds_write_b32 v2, v46 offset:624
	ds_write_b32 v2, v47 offset:888
	ds_write_b32 v2, v48 offset:128
	ds_write_b32 v2, v49 offset:392
	ds_write_b32 v2, v50 offset:656
	ds_write_b32 v2, v51 offset:920
	ds_write_b32 v2, v52 offset:160
	ds_write_b32 v2, v53 offset:424
	ds_write_b32 v2, v54 offset:688
	ds_write_b32 v2, v55 offset:952
	ds_write_b32 v2, v56 offset:192
	ds_write_b32 v2, v57 offset:456
	ds_write_b32 v2, v58 offset:720
	ds_write_b32 v2, v59 offset:984
	ds_write_b32 v2, v60 offset:224
	ds_write_b32 v2, v61 offset:488
	ds_write_b32 v2, v62 offset:752
	ds_write_b32 v2, v63 offset:1016
	s_lshr_b32 s70, s5, 2
	s_lshl_b32 s70, s70, 8
	s_and_b32 s71, s5, 3
	s_lshl_b32 s71, s71, 5
	s_add_i32 s70, s70, s71
	s_add_i32 s70, s70, s54
	s_lshl_b32 s70, s70, 12
	s_lshl_b32 s71, s4, 7
	s_add_i32 s70, s70, s71
	s_add_u32 s70, s70, 0x2200000
	s_add_u32 s70, s26, s70
	s_addc_u32 s71, s27, 0
	s_waitcnt lgkmcnt(0)
	ds_read_b64 v[160:161], v3 offset:0
	ds_read_b64 v[162:163], v3 offset:8
	ds_read_b64 v[164:165], v3 offset:16
	ds_read_b64 v[166:167], v3 offset:24
	ds_read_b64 v[168:169], v3 offset:2112
	ds_read_b64 v[170:171], v3 offset:2120
	ds_read_b64 v[172:173], v3 offset:2128
	ds_read_b64 v[174:175], v3 offset:2136
	ds_read_b64 v[176:177], v3 offset:4224
	ds_read_b64 v[178:179], v3 offset:4232
	ds_read_b64 v[180:181], v3 offset:4240
	ds_read_b64 v[182:183], v3 offset:4248
	ds_read_b64 v[184:185], v3 offset:6336
	ds_read_b64 v[186:187], v3 offset:6344
	ds_read_b64 v[188:189], v3 offset:6352
	ds_read_b64 v[190:191], v3 offset:6360
	s_waitcnt lgkmcnt(12)
	v_mul_f32_e32 v160, v160, v96
	v_mul_f32_e32 v161, v161, v97
	v_mul_f32_e32 v162, v162, v98
	v_mul_f32_e32 v163, v163, v99
	v_mul_f32_e32 v164, v164, v100
	v_mul_f32_e32 v165, v165, v101
	v_mul_f32_e32 v166, v166, v102
	v_mul_f32_e32 v167, v167, v103
	v_cvt_pk_bf16_f32 v192, v160, v161
	v_cvt_pk_bf16_f32 v193, v162, v163
	v_cvt_pk_bf16_f32 v194, v164, v165
	v_cvt_pk_bf16_f32 v195, v166, v167
	v_mov_b32_e32 v9, v4
	global_store_dwordx4 v9, v[192:195], s[70:71]
	s_waitcnt lgkmcnt(8)
	v_mul_f32_e32 v168, v168, v96
	v_mul_f32_e32 v169, v169, v97
	v_mul_f32_e32 v170, v170, v98
	v_mul_f32_e32 v171, v171, v99
	v_mul_f32_e32 v172, v172, v100
	v_mul_f32_e32 v173, v173, v101
	v_mul_f32_e32 v174, v174, v102
	v_mul_f32_e32 v175, v175, v103
	v_cvt_pk_bf16_f32 v196, v168, v169
	v_cvt_pk_bf16_f32 v197, v170, v171
	v_cvt_pk_bf16_f32 v198, v172, v173
	v_cvt_pk_bf16_f32 v199, v174, v175
	v_add_u32_e32 v9, 0x8000, v9
	global_store_dwordx4 v9, v[196:199], s[70:71]
	s_waitcnt lgkmcnt(4)
	v_mul_f32_e32 v176, v176, v96
	v_mul_f32_e32 v177, v177, v97
	v_mul_f32_e32 v178, v178, v98
	v_mul_f32_e32 v179, v179, v99
	v_mul_f32_e32 v180, v180, v100
	v_mul_f32_e32 v181, v181, v101
	v_mul_f32_e32 v182, v182, v102
	v_mul_f32_e32 v183, v183, v103
	v_cvt_pk_bf16_f32 v200, v176, v177
	v_cvt_pk_bf16_f32 v201, v178, v179
	v_cvt_pk_bf16_f32 v202, v180, v181
	v_cvt_pk_bf16_f32 v203, v182, v183
	v_add_u32_e32 v9, 0x8000, v9
	global_store_dwordx4 v9, v[200:203], s[70:71]
	s_waitcnt lgkmcnt(0)
	v_mul_f32_e32 v184, v184, v96
	v_mul_f32_e32 v185, v185, v97
	v_mul_f32_e32 v186, v186, v98
	v_mul_f32_e32 v187, v187, v99
	v_mul_f32_e32 v188, v188, v100
	v_mul_f32_e32 v189, v189, v101
	v_mul_f32_e32 v190, v190, v102
	v_mul_f32_e32 v191, v191, v103
	v_cvt_pk_bf16_f32 v204, v184, v185
	v_cvt_pk_bf16_f32 v205, v186, v187
	v_cvt_pk_bf16_f32 v206, v188, v189
	v_cvt_pk_bf16_f32 v207, v190, v191
	v_add_u32_e32 v9, 0x8000, v9
	global_store_dwordx4 v9, v[204:207], s[70:71]
	s_waitcnt vmcnt(0)
	s_waitcnt lgkmcnt(0)
	ds_write_b32 v2, v64 offset:0
	ds_write_b32 v2, v65 offset:264
	ds_write_b32 v2, v66 offset:528
	ds_write_b32 v2, v67 offset:792
	ds_write_b32 v2, v68 offset:32
	ds_write_b32 v2, v69 offset:296
	ds_write_b32 v2, v70 offset:560
	ds_write_b32 v2, v71 offset:824
	ds_write_b32 v2, v72 offset:64
	ds_write_b32 v2, v73 offset:328
	ds_write_b32 v2, v74 offset:592
	ds_write_b32 v2, v75 offset:856
	ds_write_b32 v2, v76 offset:96
	ds_write_b32 v2, v77 offset:360
	ds_write_b32 v2, v78 offset:624
	ds_write_b32 v2, v79 offset:888
	ds_write_b32 v2, v80 offset:128
	ds_write_b32 v2, v81 offset:392
	ds_write_b32 v2, v82 offset:656
	ds_write_b32 v2, v83 offset:920
	ds_write_b32 v2, v84 offset:160
	ds_write_b32 v2, v85 offset:424
	ds_write_b32 v2, v86 offset:688
	ds_write_b32 v2, v87 offset:952
	ds_write_b32 v2, v88 offset:192
	ds_write_b32 v2, v89 offset:456
	ds_write_b32 v2, v90 offset:720
	ds_write_b32 v2, v91 offset:984
	ds_write_b32 v2, v92 offset:224
	ds_write_b32 v2, v93 offset:488
	ds_write_b32 v2, v94 offset:752
	ds_write_b32 v2, v95 offset:1016
	s_lshr_b32 s70, s67, 2
	s_lshl_b32 s70, s70, 8
	s_and_b32 s71, s67, 3
	s_lshl_b32 s71, s71, 5
	s_add_i32 s70, s70, s71
	s_add_i32 s70, s70, s40
	s_lshl_b32 s70, s70, 12
	s_lshl_b32 s71, s55, 7
	s_add_i32 s70, s70, s71
	s_add_u32 s70, s70, 0x2200000
	s_add_u32 s70, s26, s70
	s_addc_u32 s71, s27, 0
	s_waitcnt lgkmcnt(0)
	ds_read_b64 v[160:161], v3 offset:0
	ds_read_b64 v[162:163], v3 offset:8
	ds_read_b64 v[164:165], v3 offset:16
	ds_read_b64 v[166:167], v3 offset:24
	ds_read_b64 v[168:169], v3 offset:2112
	ds_read_b64 v[170:171], v3 offset:2120
	ds_read_b64 v[172:173], v3 offset:2128
	ds_read_b64 v[174:175], v3 offset:2136
	ds_read_b64 v[176:177], v3 offset:4224
	ds_read_b64 v[178:179], v3 offset:4232
	ds_read_b64 v[180:181], v3 offset:4240
	ds_read_b64 v[182:183], v3 offset:4248
	ds_read_b64 v[184:185], v3 offset:6336
	ds_read_b64 v[186:187], v3 offset:6344
	ds_read_b64 v[188:189], v3 offset:6352
	ds_read_b64 v[190:191], v3 offset:6360
	s_waitcnt lgkmcnt(12)
	v_mul_f32_e32 v160, v160, v104
	v_mul_f32_e32 v161, v161, v105
	v_mul_f32_e32 v162, v162, v106
	v_mul_f32_e32 v163, v163, v107
	v_mul_f32_e32 v164, v164, v108
	v_mul_f32_e32 v165, v165, v109
	v_mul_f32_e32 v166, v166, v110
	v_mul_f32_e32 v167, v167, v111
	v_cvt_pk_bf16_f32 v192, v160, v161
	v_cvt_pk_bf16_f32 v193, v162, v163
	v_cvt_pk_bf16_f32 v194, v164, v165
	v_cvt_pk_bf16_f32 v195, v166, v167
	v_mov_b32_e32 v9, v4
	global_store_dwordx4 v9, v[192:195], s[70:71]
	s_waitcnt lgkmcnt(8)
	v_mul_f32_e32 v168, v168, v104
	v_mul_f32_e32 v169, v169, v105
	v_mul_f32_e32 v170, v170, v106
	v_mul_f32_e32 v171, v171, v107
	v_mul_f32_e32 v172, v172, v108
	v_mul_f32_e32 v173, v173, v109
	v_mul_f32_e32 v174, v174, v110
	v_mul_f32_e32 v175, v175, v111
	v_cvt_pk_bf16_f32 v196, v168, v169
	v_cvt_pk_bf16_f32 v197, v170, v171
	v_cvt_pk_bf16_f32 v198, v172, v173
	v_cvt_pk_bf16_f32 v199, v174, v175
	v_add_u32_e32 v9, 0x8000, v9
	global_store_dwordx4 v9, v[196:199], s[70:71]
	s_waitcnt lgkmcnt(4)
	v_mul_f32_e32 v176, v176, v104
	v_mul_f32_e32 v177, v177, v105
	v_mul_f32_e32 v178, v178, v106
	v_mul_f32_e32 v179, v179, v107
	v_mul_f32_e32 v180, v180, v108
	v_mul_f32_e32 v181, v181, v109
	v_mul_f32_e32 v182, v182, v110
	v_mul_f32_e32 v183, v183, v111
	v_cvt_pk_bf16_f32 v200, v176, v177
	v_cvt_pk_bf16_f32 v201, v178, v179
	v_cvt_pk_bf16_f32 v202, v180, v181
	v_cvt_pk_bf16_f32 v203, v182, v183
	v_add_u32_e32 v9, 0x8000, v9
	global_store_dwordx4 v9, v[200:203], s[70:71]
	s_waitcnt lgkmcnt(0)
	v_mul_f32_e32 v184, v184, v104
	v_mul_f32_e32 v185, v185, v105
	v_mul_f32_e32 v186, v186, v106
	v_mul_f32_e32 v187, v187, v107
	v_mul_f32_e32 v188, v188, v108
	v_mul_f32_e32 v189, v189, v109
	v_mul_f32_e32 v190, v190, v110
	v_mul_f32_e32 v191, v191, v111
	v_cvt_pk_bf16_f32 v204, v184, v185
	v_cvt_pk_bf16_f32 v205, v186, v187
	v_cvt_pk_bf16_f32 v206, v188, v189
	v_cvt_pk_bf16_f32 v207, v190, v191
	v_add_u32_e32 v9, 0x8000, v9
	global_store_dwordx4 v9, v[204:207], s[70:71]
	s_waitcnt vmcnt(0) lgkmcnt(0)
